# grid barrier: followers poll the top generation word directly (no per-XCD relay hop)
# baseline (speedup 1.0000x reference)
; __device__ __forceinline__ unsigned xb_ld(unsigned* p)              { return __hip_atomic_load(p, __ATOMIC_RELAXED, __HIP_MEMORY_SCOPE_AGENT); }
; __device__ __forceinline__ unsigned xb_add(unsigned* p, unsigned v) { return __hip_atomic_fetch_add(p, v, __ATOMIC_RELAXED, __HIP_MEMORY_SCOPE_AGENT); }
; #define XB_SPIN(cond, bar) do { unsigned _sp = 0; while (cond) { __builtin_amdgcn_s_sleep(1); \
;     if ((++_sp & 255u) == 0u) { if (xb_ld(&(bar)[XB_TMO])) break; if (_sp > XB_SPIN_CAP) { atomicAdd(&(bar)[XB_TMO], 1u); break; } } } } while (0)
; __device__ __forceinline__ void xcd_barrier(const XcdBarrier& b) {
;     ...
;         const unsigned old = xb_add(&bar[XB_XSUB(b.x)], 1u);
;         const unsigned gen = old / nloc;
;         if (old + 1u == (gen + 1u) * nloc) {
;             __builtin_amdgcn_fence(__ATOMIC_RELEASE, "agent");
;             asm volatile("s_waitcnt vmcnt(0)" ::: "memory");
;             const unsigned og = xb_add(&bar[XB_TOP], 1u);
;             const unsigned tg = og / nx;
;             if (og + 1u == (tg + 1u) * nx) xb_add(&bar[XB_TOPGEN], 1u);
;             else XB_SPIN(xb_ld(&bar[XB_TOPGEN]) == tg, bar);
;             __builtin_amdgcn_fence(__ATOMIC_ACQUIRE, "agent");
;             xb_add(&bar[XB_XGEN(b.x)], 1u);
;             asm volatile("s_waitcnt vmcnt(0)" ::: "memory");
;         } else {
;             XB_SPIN(xb_ld(&bar[XB_XGEN(b.x)]) == gen, bar);
.LBB0_145:
	s_or_b64 exec, exec, s[10:11]
	v_cvt_f32_u32_e32 v5, v3
	s_waitcnt vmcnt(0)
	v_readfirstlane_b32 s8, v4
	v_sub_u32_e32 v4, 0, v3
	v_rcp_iflag_f32_e32 v5, v5
	v_add_u32_e32 v6, s8, v2
	v_mul_f32_e32 v5, 0x4f7ffffe, v5
	v_cvt_u32_f32_e32 v5, v5
	v_mul_lo_u32 v2, v4, v5
	v_mul_hi_u32 v2, v5, v2
	v_add_u32_e32 v2, v5, v2
	v_mul_hi_u32 v2, v6, v2
	v_mul_lo_u32 v4, v2, v3
	v_sub_u32_e32 v4, v6, v4
	v_add_u32_e32 v5, 1, v2
	v_cmp_ge_u32_e32 vcc, v4, v3
	s_nop 1
	v_cndmask_b32_e32 v2, v2, v5, vcc
	v_sub_u32_e32 v5, v4, v3
	v_cndmask_b32_e32 v4, v4, v5, vcc
	v_add_u32_e32 v5, 1, v2
	v_cmp_ge_u32_e32 vcc, v4, v3
	v_add_u32_e32 v4, 1, v6
	s_nop 0
	v_cndmask_b32_e32 v2, v2, v5, vcc
	v_mul_lo_u32 v5, v3, v2
	v_add_u32_e32 v3, v5, v3
	v_cmp_ne_u32_e32 vcc, v4, v3
	s_and_saveexec_b64 s[8:9], vcc
	s_xor_b64 s[8:9], exec, s[8:9]
	s_cbranch_execz .LBB0_159
	buffer_inv sc1
	s_movk_i32 s10, 0xd40
	s_mov_b32 s11, 0
	s_lshl_b64 s[10:11], s[10:11], 2
	s_add_u32 s14, s26, s10
	s_addc_u32 s15, s27, s11
	s_waitcnt lgkmcnt(0)
	v_mov_b32_e32 v1, 0
	global_load_dword v3, v1, s[14:15] sc1
	s_waitcnt vmcnt(0)
	v_cmp_eq_u32_e32 vcc, v3, v2
	s_and_saveexec_b64 s[10:11], vcc
	s_cbranch_execz .LBB0_158
	s_add_u32 s12, s6, 0xc0200
	s_addc_u32 s13, s7, 0
	s_mov_b32 s29, 1
	s_mov_b64 s[16:17], 0
	s_branch .LBB0_149

; __device__ __forceinline__ unsigned xb_ld(unsigned* p)              { return __hip_atomic_load(p, __ATOMIC_RELAXED, __HIP_MEMORY_SCOPE_AGENT); }
; __device__ __forceinline__ unsigned xb_add(unsigned* p, unsigned v) { return __hip_atomic_fetch_add(p, v, __ATOMIC_RELAXED, __HIP_MEMORY_SCOPE_AGENT); }
; #define XB_SPIN(cond, bar) do { unsigned _sp = 0; while (cond) { __builtin_amdgcn_s_sleep(1); \
;     if ((++_sp & 255u) == 0u) { if (xb_ld(&(bar)[XB_TMO])) break; if (_sp > XB_SPIN_CAP) { atomicAdd(&(bar)[XB_TMO], 1u); break; } } } } while (0)
; __device__ __forceinline__ void xcd_barrier(const XcdBarrier& b) {
;     ...
;         const unsigned old = xb_add(&bar[XB_XSUB(b.x)], 1u);
;         const unsigned gen = old / nloc;
;         if (old + 1u == (gen + 1u) * nloc) {
;             __builtin_amdgcn_fence(__ATOMIC_RELEASE, "agent");
;             asm volatile("s_waitcnt vmcnt(0)" ::: "memory");
;             const unsigned og = xb_add(&bar[XB_TOP], 1u);
;             const unsigned tg = og / nx;
;             if (og + 1u == (tg + 1u) * nx) xb_add(&bar[XB_TOPGEN], 1u);
;             else XB_SPIN(xb_ld(&bar[XB_TOPGEN]) == tg, bar);
;             __builtin_amdgcn_fence(__ATOMIC_ACQUIRE, "agent");
;             xb_add(&bar[XB_XGEN(b.x)], 1u);
;             asm volatile("s_waitcnt vmcnt(0)" ::: "memory");
;         } else {
;             XB_SPIN(xb_ld(&bar[XB_XGEN(b.x)]) == gen, bar);
.LBB0_255:
	s_or_b64 exec, exec, s[10:11]
	v_cvt_f32_u32_e32 v6, v4
	s_waitcnt vmcnt(0)
	v_readfirstlane_b32 s8, v5
	v_sub_u32_e32 v5, 0, v4
	v_rcp_iflag_f32_e32 v6, v6
	v_add_u32_e32 v7, s8, v3
	v_mul_f32_e32 v6, 0x4f7ffffe, v6
	v_cvt_u32_f32_e32 v6, v6
	v_mul_lo_u32 v3, v5, v6
	v_mul_hi_u32 v3, v6, v3
	v_add_u32_e32 v3, v6, v3
	v_mul_hi_u32 v3, v7, v3
	v_mul_lo_u32 v5, v3, v4
	v_sub_u32_e32 v5, v7, v5
	v_add_u32_e32 v6, 1, v3
	v_cmp_ge_u32_e32 vcc, v5, v4
	s_nop 1
	v_cndmask_b32_e32 v3, v3, v6, vcc
	v_sub_u32_e32 v6, v5, v4
	v_cndmask_b32_e32 v5, v5, v6, vcc
	v_add_u32_e32 v6, 1, v3
	v_cmp_ge_u32_e32 vcc, v5, v4
	v_add_u32_e32 v5, 1, v7
	s_nop 0
	v_cndmask_b32_e32 v3, v3, v6, vcc
	v_mul_lo_u32 v6, v4, v3
	v_add_u32_e32 v4, v6, v4
	v_cmp_ne_u32_e32 vcc, v5, v4
	s_and_saveexec_b64 s[8:9], vcc
	s_xor_b64 s[8:9], exec, s[8:9]
	s_cbranch_execz .LBB0_269
	buffer_inv sc1
	s_movk_i32 s10, 0xd40
	s_mov_b32 s11, 0
	s_lshl_b64 s[10:11], s[10:11], 2
	s_add_u32 s14, s26, s10
	s_addc_u32 s15, s27, s11
	s_waitcnt lgkmcnt(0)
	v_mov_b32_e32 v2, 0
	global_load_dword v4, v2, s[14:15] sc1
	s_waitcnt vmcnt(0)
	v_cmp_eq_u32_e32 vcc, v4, v3
	s_and_saveexec_b64 s[10:11], vcc
	s_cbranch_execz .LBB0_268
	s_add_u32 s12, s6, 0xc0200
	s_addc_u32 s13, s7, 0
	s_mov_b32 s29, 1
	s_mov_b64 s[16:17], 0
	s_branch .LBB0_259

; __device__ __forceinline__ unsigned xb_ld(unsigned* p)              { return __hip_atomic_load(p, __ATOMIC_RELAXED, __HIP_MEMORY_SCOPE_AGENT); }
; __device__ __forceinline__ unsigned xb_add(unsigned* p, unsigned v) { return __hip_atomic_fetch_add(p, v, __ATOMIC_RELAXED, __HIP_MEMORY_SCOPE_AGENT); }
; #define XB_SPIN(cond, bar) do { unsigned _sp = 0; while (cond) { __builtin_amdgcn_s_sleep(1); \
;     if ((++_sp & 255u) == 0u) { if (xb_ld(&(bar)[XB_TMO])) break; if (_sp > XB_SPIN_CAP) { atomicAdd(&(bar)[XB_TMO], 1u); break; } } } } while (0)
; __device__ __forceinline__ void xcd_barrier(const XcdBarrier& b) {
;     ...
;         const unsigned old = xb_add(&bar[XB_XSUB(b.x)], 1u);
;         const unsigned gen = old / nloc;
;         if (old + 1u == (gen + 1u) * nloc) {
;             __builtin_amdgcn_fence(__ATOMIC_RELEASE, "agent");
;             asm volatile("s_waitcnt vmcnt(0)" ::: "memory");
;             const unsigned og = xb_add(&bar[XB_TOP], 1u);
;             const unsigned tg = og / nx;
;             if (og + 1u == (tg + 1u) * nx) xb_add(&bar[XB_TOPGEN], 1u);
;             else XB_SPIN(xb_ld(&bar[XB_TOPGEN]) == tg, bar);
;             __builtin_amdgcn_fence(__ATOMIC_ACQUIRE, "agent");
;             xb_add(&bar[XB_XGEN(b.x)], 1u);
;             asm volatile("s_waitcnt vmcnt(0)" ::: "memory");
;         } else {
;             XB_SPIN(xb_ld(&bar[XB_XGEN(b.x)]) == gen, bar);
.LBB0_1619:
	s_or_b64 exec, exec, s[16:17]
	v_cvt_f32_u32_e32 v6, v4
	s_waitcnt vmcnt(0)
	v_readfirstlane_b32 s10, v5
	v_sub_u32_e32 v5, 0, v4
	v_rcp_iflag_f32_e32 v6, v6
	v_add_u32_e32 v7, s10, v3
	v_mul_f32_e32 v6, 0x4f7ffffe, v6
	v_cvt_u32_f32_e32 v6, v6
	v_mul_lo_u32 v3, v5, v6
	v_mul_hi_u32 v3, v6, v3
	v_add_u32_e32 v3, v6, v3
	v_mul_hi_u32 v3, v7, v3
	v_mul_lo_u32 v5, v3, v4
	v_sub_u32_e32 v5, v7, v5
	v_add_u32_e32 v6, 1, v3
	v_cmp_ge_u32_e32 vcc, v5, v4
	s_nop 1
	v_cndmask_b32_e32 v3, v3, v6, vcc
	v_sub_u32_e32 v6, v5, v4
	v_cndmask_b32_e32 v5, v5, v6, vcc
	v_add_u32_e32 v6, 1, v3
	v_cmp_ge_u32_e32 vcc, v5, v4
	v_add_u32_e32 v5, 1, v7
	s_nop 0
	v_cndmask_b32_e32 v3, v3, v6, vcc
	v_mul_lo_u32 v6, v4, v3
	v_add_u32_e32 v4, v6, v4
	v_cmp_ne_u32_e32 vcc, v5, v4
	s_and_saveexec_b64 s[10:11], vcc
	s_xor_b64 s[10:11], exec, s[10:11]
	s_cbranch_execz .LBB0_1633
	buffer_inv sc1
	s_movk_i32 s16, 0xd40
	s_mov_b32 s17, 0
	s_lshl_b64 s[16:17], s[16:17], 2
	s_add_u32 s20, s34, s16
	s_addc_u32 s21, s35, s17
	s_waitcnt lgkmcnt(0)
	v_mov_b32_e32 v2, 0
	global_load_dword v4, v2, s[20:21] sc1
	s_waitcnt vmcnt(0)
	v_cmp_eq_u32_e32 vcc, v4, v3
	s_and_saveexec_b64 s[16:17], vcc
	s_cbranch_execz .LBB0_1632
	s_add_u32 s18, s8, 0xc0200
	s_addc_u32 s19, s9, 0
	s_mov_b32 s37, 1
	s_mov_b64 s[22:23], 0
	s_branch .LBB0_1623

; __device__ __forceinline__ unsigned xb_ld(unsigned* p)              { return __hip_atomic_load(p, __ATOMIC_RELAXED, __HIP_MEMORY_SCOPE_AGENT); }
; __device__ __forceinline__ unsigned xb_add(unsigned* p, unsigned v) { return __hip_atomic_fetch_add(p, v, __ATOMIC_RELAXED, __HIP_MEMORY_SCOPE_AGENT); }
; #define XB_SPIN(cond, bar) do { unsigned _sp = 0; while (cond) { __builtin_amdgcn_s_sleep(1); \
;     if ((++_sp & 255u) == 0u) { if (xb_ld(&(bar)[XB_TMO])) break; if (_sp > XB_SPIN_CAP) { atomicAdd(&(bar)[XB_TMO], 1u); break; } } } } while (0)
; __device__ __forceinline__ void xcd_barrier(const XcdBarrier& b) {
;     ...
;         const unsigned old = xb_add(&bar[XB_XSUB(b.x)], 1u);
;         const unsigned gen = old / nloc;
;         if (old + 1u == (gen + 1u) * nloc) {
;             __builtin_amdgcn_fence(__ATOMIC_RELEASE, "agent");
;             asm volatile("s_waitcnt vmcnt(0)" ::: "memory");
;             const unsigned og = xb_add(&bar[XB_TOP], 1u);
;             const unsigned tg = og / nx;
;             if (og + 1u == (tg + 1u) * nx) xb_add(&bar[XB_TOPGEN], 1u);
;             else XB_SPIN(xb_ld(&bar[XB_TOPGEN]) == tg, bar);
;             __builtin_amdgcn_fence(__ATOMIC_ACQUIRE, "agent");
;             xb_add(&bar[XB_XGEN(b.x)], 1u);
;             asm volatile("s_waitcnt vmcnt(0)" ::: "memory");
;         } else {
;             XB_SPIN(xb_ld(&bar[XB_XGEN(b.x)]) == gen, bar);
.LBB0_3173:
	s_or_b64 exec, exec, s[10:11]
	v_cvt_f32_u32_e32 v6, v4
	s_waitcnt vmcnt(0)
	v_readfirstlane_b32 s8, v5
	v_sub_u32_e32 v5, 0, v4
	v_rcp_iflag_f32_e32 v6, v6
	v_add_u32_e32 v7, s8, v3
	v_mul_f32_e32 v6, 0x4f7ffffe, v6
	v_cvt_u32_f32_e32 v6, v6
	v_mul_lo_u32 v3, v5, v6
	v_mul_hi_u32 v3, v6, v3
	v_add_u32_e32 v3, v6, v3
	v_mul_hi_u32 v3, v7, v3
	v_mul_lo_u32 v5, v3, v4
	v_sub_u32_e32 v5, v7, v5
	v_add_u32_e32 v6, 1, v3
	v_cmp_ge_u32_e32 vcc, v5, v4
	s_nop 1
	v_cndmask_b32_e32 v3, v3, v6, vcc
	v_sub_u32_e32 v6, v5, v4
	v_cndmask_b32_e32 v5, v5, v6, vcc
	v_add_u32_e32 v6, 1, v3
	v_cmp_ge_u32_e32 vcc, v5, v4
	v_add_u32_e32 v5, 1, v7
	s_nop 0
	v_cndmask_b32_e32 v3, v3, v6, vcc
	v_mul_lo_u32 v6, v4, v3
	v_add_u32_e32 v4, v6, v4
	v_cmp_ne_u32_e32 vcc, v5, v4
	s_and_saveexec_b64 s[8:9], vcc
	s_xor_b64 s[8:9], exec, s[8:9]
	s_cbranch_execz .LBB0_3187
	buffer_inv sc1
	s_movk_i32 s10, 0xd40
	s_mov_b32 s11, 0
	s_lshl_b64 s[10:11], s[10:11], 2
	s_add_u32 s16, s28, s10
	s_addc_u32 s17, s29, s11
	s_waitcnt lgkmcnt(0)
	v_mov_b32_e32 v2, 0
	global_load_dword v4, v2, s[16:17] sc1
	s_waitcnt vmcnt(0)
	v_cmp_eq_u32_e32 vcc, v4, v3
	s_and_saveexec_b64 s[10:11], vcc
	s_cbranch_execz .LBB0_3186
	s_add_u32 s14, s6, 0xc0200
	s_addc_u32 s15, s7, 0
	s_mov_b32 s31, 1
	s_mov_b64 s[18:19], 0
	s_branch .LBB0_3177
